# LN wave reductions: xor-8/4/2/1 steps via DPP adds (bit-identical butterfly)
# baseline (speedup 1.0000x reference)
; DI float wave_sum(float v) {
; #pragma unroll
;   for (int o = 32; o >= 1; o >>= 1) v += __shfl_xor(v, o);
;   return v;
; DI void phase_ln(const Params& p, const float* g, const float* b, bool final_ln) {
;     ...
;   for (int row = blockIdx.x * 8 + wave; row < T; row += gridDim.x * 8) {
;     float* xr = X + (size_t)row * D;
;     float4 v[4];
;     float s = 0.f;
; #pragma unroll
;     for (int i = 0; i < 4; ++i) {
;       const unsigned long long raw = __builtin_nontemporal_load((const unsigned long long*)(r16 + (size_t)row * D + i * 256 + lane * 4));
;       v[i].x = (float)__builtin_bit_cast(_Float16, (u16)(raw & 0xffffu));
;       v[i].y = (float)__builtin_bit_cast(_Float16, (u16)((raw >> 16) & 0xffffu));
;       v[i].z = (float)__builtin_bit_cast(_Float16, (u16)((raw >> 32) & 0xffffu));
;       v[i].w = (float)__builtin_bit_cast(_Float16, (u16)(raw >> 48));
;       s += v[i].x + v[i].y + v[i].z + v[i].w;
;     }
;     const float mean = wave_sum(s) * (1.f / D);
;     float q = 0.f;
; #pragma unroll
;     for (int i = 0; i < 4; ++i) {
;       v[i].x -= mean; v[i].y -= mean; v[i].z -= mean; v[i].w -= mean;
;       q += v[i].x * v[i].x + v[i].y * v[i].y + v[i].z * v[i].z + v[i].w * v[i].w;
;     }
;     const float rstd = rsqrtf(wave_sum(q) * (1.f / D) + 1e-5f);
.LBB0_793:
	s_waitcnt vmcnt(4)
	v_mov_b32_e32 v36, v72
	v_mov_b32_e32 v37, v73
	v_mov_b32_e32 v46, v74
	v_mov_b32_e32 v47, v75
	v_mov_b32_e32 v48, v76
	v_mov_b32_e32 v49, v77
	v_mov_b32_e32 v50, v78
	v_mov_b32_e32 v51, v79
	v_add_u32_e32 v88, s72, v38
	v_min_i32_e32 v88, 0x7fff, v88
	v_ashrrev_i32_e32 v89, 31, v88
	v_lshlrev_b64 v[88:89], 11, v[88:89]
	v_lshl_add_u64 v[88:89], v[40:41], 0, v[88:89]
	global_load_dwordx2 v[72:73], v[88:89], off nt
	global_load_dwordx2 v[74:75], v[88:89], off offset:512 nt
	global_load_dwordx2 v[76:77], v[88:89], off offset:1024 nt
	global_load_dwordx2 v[78:79], v[88:89], off offset:1536 nt
	v_cvt_f32_f16_e32 v62, v36
	v_cvt_f32_f16_sdwa v63, v36 dst_sel:DWORD dst_unused:UNUSED_PAD src0_sel:WORD_1
	v_cvt_f32_f16_e32 v56, v48
	v_cvt_f32_f16_e32 v52, v50
	v_cvt_f32_f16_sdwa v53, v50 dst_sel:DWORD dst_unused:UNUSED_PAD src0_sel:WORD_1
	v_cvt_f32_f16_sdwa v57, v48 dst_sel:DWORD dst_unused:UNUSED_PAD src0_sel:WORD_1
	v_cvt_f32_f16_e32 v34, v51
	v_cvt_f32_f16_e32 v54, v49
	v_cvt_f32_f16_sdwa v35, v51 dst_sel:DWORD dst_unused:UNUSED_PAD src0_sel:WORD_1
	v_cvt_f32_f16_sdwa v55, v49 dst_sel:DWORD dst_unused:UNUSED_PAD src0_sel:WORD_1
	v_mov_b32_e32 v48, v56
	v_mov_b32_e32 v49, v52
	v_mov_b32_e32 v50, v57
	v_mov_b32_e32 v51, v53
	v_pk_add_f32 v[48:49], v[48:49], v[50:51]
	v_mov_b32_e32 v50, v54
	v_mov_b32_e32 v51, v34
	v_pk_add_f32 v[48:49], v[48:49], v[50:51]
	v_mov_b32_e32 v50, v55
	v_mov_b32_e32 v51, v35
	v_pk_add_f32 v[48:49], v[48:49], v[50:51]
	v_cvt_f32_f16_e32 v50, v46
	v_cvt_f32_f16_sdwa v51, v46 dst_sel:DWORD dst_unused:UNUSED_PAD src0_sel:WORD_1
	v_cvt_f32_f16_e32 v58, v47
	v_cvt_f32_f16_e32 v60, v37
	v_cvt_f32_f16_sdwa v59, v47 dst_sel:DWORD dst_unused:UNUSED_PAD src0_sel:WORD_1
	v_cvt_f32_f16_sdwa v61, v37 dst_sel:DWORD dst_unused:UNUSED_PAD src0_sel:WORD_1
	v_mov_b32_e32 v36, v62
	v_mov_b32_e32 v37, v50
	v_mov_b32_e32 v70, v63
	v_mov_b32_e32 v71, v51
	v_pk_add_f32 v[36:37], v[36:37], v[70:71]
	v_mov_b32_e32 v70, v60
	v_mov_b32_e32 v71, v58
	v_pk_add_f32 v[36:37], v[36:37], v[70:71]
	v_mov_b32_e32 v70, v61
	v_mov_b32_e32 v71, v59
	v_pk_add_f32 v[36:37], v[36:37], v[70:71]
	v_lshlrev_b64 v[46:47], 12, v[38:39]
	v_add_f32_e32 v0, 0, v36
	v_add_f32_e32 v0, v0, v37
	v_add_f32_e32 v0, v0, v48
	v_add_f32_e32 v0, v0, v49
	ds_bpermute_b32 v36, v64, v0
	v_lshl_add_u64 v[46:47], v[44:45], 0, v[46:47]
	s_waitcnt lgkmcnt(0)
	v_add_f32_e32 v0, v0, v36
	ds_bpermute_b32 v36, v65, v0
	s_waitcnt lgkmcnt(0)
	v_add_f32_e32 v0, v0, v36
	s_nop 1
	v_add_f32_dpp v0, v0, v0 row_ror:8 row_mask:0xf bank_mask:0xf
	s_nop 1
	v_add_f32_dpp v0, v0, v0 row_ror:4 row_mask:0xf bank_mask:0xf
	s_nop 1
	v_add_f32_dpp v0, v0, v0 row_ror:2 row_mask:0xf bank_mask:0xf
	s_nop 1
	v_add_f32_dpp v0, v0, v0 quad_perm:[1,0,3,2] row_mask:0xf bank_mask:0xf
	v_mul_f32_e32 v0, 0x3a800000, v0
	v_pk_add_f32 v[36:37], v[62:63], v[0:1] op_sel_hi:[1,0] neg_lo:[0,1] neg_hi:[0,1]
	v_pk_add_f32 v[50:51], v[50:51], v[0:1] op_sel_hi:[1,0] neg_lo:[0,1] neg_hi:[0,1]
	v_pk_add_f32 v[62:63], v[60:61], v[0:1] op_sel_hi:[1,0] neg_lo:[0,1] neg_hi:[0,1]
	v_mov_b32_e32 v60, v37
	v_mov_b32_e32 v61, v51
	v_pk_add_f32 v[48:49], v[58:59], v[0:1] op_sel_hi:[1,0] neg_lo:[0,1] neg_hi:[0,1]
	v_mov_b32_e32 v58, v36
	v_mov_b32_e32 v59, v50
	v_pk_mul_f32 v[60:61], v[60:61], v[60:61]
	s_nop 0
	v_pk_fma_f32 v[58:59], v[58:59], v[58:59], v[60:61]
	v_mov_b32_e32 v60, v62
	v_mov_b32_e32 v61, v48
	v_pk_fma_f32 v[58:59], v[60:61], v[60:61], v[58:59]
	v_mov_b32_e32 v60, v63
	v_mov_b32_e32 v61, v49
	v_pk_fma_f32 v[60:61], v[60:61], v[60:61], v[58:59]
	v_pk_add_f32 v[58:59], v[56:57], v[0:1] op_sel_hi:[1,0] neg_lo:[0,1] neg_hi:[0,1]
	v_pk_add_f32 v[56:57], v[54:55], v[0:1] op_sel_hi:[1,0] neg_lo:[0,1] neg_hi:[0,1]
	v_pk_add_f32 v[54:55], v[52:53], v[0:1] op_sel_hi:[1,0] neg_lo:[0,1] neg_hi:[0,1]
	v_mov_b32_e32 v71, v59
	v_mov_b32_e32 v70, v55
	v_pk_add_f32 v[52:53], v[34:35], v[0:1] op_sel_hi:[1,0] neg_lo:[0,1] neg_hi:[0,1]
	v_mov_b32_e32 v34, v54
	v_mov_b32_e32 v35, v58
	v_pk_mul_f32 v[70:71], v[70:71], v[70:71]
	v_add_f32_e32 v0, v60, v61
	v_pk_fma_f32 v[34:35], v[34:35], v[34:35], v[70:71]
	v_mov_b32_e32 v70, v52
	v_mov_b32_e32 v71, v56
	v_pk_fma_f32 v[34:35], v[70:71], v[70:71], v[34:35]
	v_mov_b32_e32 v70, v53
	v_mov_b32_e32 v71, v57
	v_pk_fma_f32 v[34:35], v[70:71], v[70:71], v[34:35]
	s_nop 0
	v_add_f32_e32 v0, v35, v0
	v_add_f32_e32 v0, v34, v0
	ds_bpermute_b32 v34, v64, v0
	s_waitcnt lgkmcnt(0)
	v_add_f32_e32 v0, v0, v34
	ds_bpermute_b32 v34, v65, v0
	s_waitcnt lgkmcnt(0)
	v_add_f32_e32 v0, v0, v34
	s_nop 1
	v_add_f32_dpp v0, v0, v0 row_ror:8 row_mask:0xf bank_mask:0xf
	s_nop 1
	v_add_f32_dpp v0, v0, v0 row_ror:4 row_mask:0xf bank_mask:0xf
	s_nop 1
	v_add_f32_dpp v0, v0, v0 row_ror:2 row_mask:0xf bank_mask:0xf
	s_nop 1
	v_add_f32_dpp v0, v0, v0 quad_perm:[1,0,3,2] row_mask:0xf bank_mask:0xf
	v_fmamk_f32 v0, v0, 0x3a800000, v200
	v_cmp_gt_f32_e32 vcc, s19, v0
	v_mul_f32_e32 v34, 0x4b800000, v0
	s_nop 0
	v_cndmask_b32_e32 v0, v0, v34, vcc
	v_rsq_f32_e32 v0, v0
	s_nop 0
	v_mul_f32_e32 v34, 0x45800000, v0
	v_cndmask_b32_e32 v60, v0, v34, vcc
	v_pk_mul_f32 v[34:35], v[36:37], v[60:61] op_sel_hi:[1,0]
	v_pk_mul_f32 v[36:37], v[62:63], v[60:61] op_sel_hi:[1,0]
	v_cndmask_b32_e64 v0, 0, 1, s[14:15]
	v_pk_fma_f32 v[34:35], v[2:3], v[34:35], v[10:11]
	v_pk_fma_f32 v[36:37], v[4:5], v[36:37], v[12:13]
	v_cmp_ne_u32_e64 s[8:9], 1, v0
	s_andn2_b64 vcc, exec, s[14:15]
	s_cbranch_vccnz .LBB0_795
	global_store_dwordx4 v[46:47], v[34:37], off
